# A/B epilogue LayerNorm apply: (x-mu)*rstd -> fma(x, rstd, -mu*rstd), 32 VALU fewer per wave-item
# speedup vs baseline: 1.0117x; 1.0025x over previous
.LBB0_840:
	s_or_b64 exec, exec, s[10:11]
	s_nop 0
	v_mov_b32_e32 v94, v155
	v_mov_b32_e32 v95, v83
	v_pk_mul_f32 v[90:91], v[82:83], v[82:83]
	v_pk_add_f32 v[94:95], v[82:83], v[94:95]
	v_pk_mul_f32 v[92:93], v[84:85], v[84:85]
	v_pk_mov_b32 v[94:95], v[90:91], v[94:95] op_sel:[1,0]
	v_mov_b32_e32 v91, v83
	v_pk_add_f32 v[90:91], v[90:91], v[94:95]
	v_mov_b32_e32 v94, v92
	v_mov_b32_e32 v95, v84
	v_pk_add_f32 v[90:91], v[90:91], v[94:95]
	v_mov_b32_e32 v92, v93
	v_mov_b32_e32 v93, v85
	v_pk_add_f32 v[92:93], v[92:93], v[90:91]
	v_add_f32_e32 v90, 0, v140
	v_add_f32_e32 v90, v141, v90
	v_add_f32_e32 v99, v142, v90
	v_mov_b32_e32 v90, v140
	v_mov_b32_e32 v91, v142
	v_mul_f32_e32 v98, v141, v141
	v_pk_fma_f32 v[90:91], v[90:91], v[90:91], v[98:99] op_sel_hi:[1,1,0]
	v_mul_f32_e32 v98, v142, v142
	v_pk_add_f32 v[90:91], v[90:91], v[98:99] op_sel_hi:[1,0]
	v_add_f32_e32 v98, v143, v99
	v_add_f32_e32 v101, v144, v98
	v_mul_f32_e32 v100, v143, v143
	v_mov_b32_e32 v98, v144
	v_mov_b32_e32 v99, v143
	v_pk_add_f32 v[90:91], v[100:101], v[90:91] op_sel_hi:[0,1]
	v_pk_fma_f32 v[90:91], v[98:99], v[98:99], v[90:91]
	v_add_f32_e32 v98, v145, v101
	v_add_f32_e32 v99, v146, v98
	v_mul_f32_e32 v98, v145, v145
	v_mov_b32_e32 v100, v146
	v_mov_b32_e32 v101, v145
	v_pk_add_f32 v[90:91], v[98:99], v[90:91] op_sel_hi:[0,1]
	v_pk_fma_f32 v[100:101], v[100:101], v[100:101], v[90:91]
	v_add_f32_e32 v90, 0, v132
	v_add_f32_e32 v90, v133, v90
	v_add_f32_e32 v101, v134, v90
	v_mov_b32_e32 v90, v132
	v_mov_b32_e32 v91, v134
	v_mul_f32_e32 v98, v133, v133
	v_pk_fma_f32 v[90:91], v[90:91], v[90:91], v[98:99] op_sel_hi:[1,1,0]
	v_mul_f32_e32 v98, v134, v134
	v_pk_add_f32 v[90:91], v[90:91], v[98:99] op_sel_hi:[1,0]
	v_add_f32_e32 v98, v135, v101
	v_add_f32_e32 v101, v136, v98
	v_mul_f32_e32 v98, v135, v135
	v_mov_b32_e32 v102, v136
	v_mov_b32_e32 v103, v135
	v_pk_add_f32 v[90:91], v[98:99], v[90:91] op_sel_hi:[0,1]
	v_add_f32_e32 v98, v137, v101
	v_pk_fma_f32 v[90:91], v[102:103], v[102:103], v[90:91]
	v_add_f32_e32 v103, v138, v98
	v_mul_f32_e32 v98, v137, v137
	v_mov_b32_e32 v104, v138
	v_mov_b32_e32 v105, v137
	v_pk_add_f32 v[90:91], v[98:99], v[90:91] op_sel_hi:[0,1]
	v_pk_fma_f32 v[104:105], v[104:105], v[104:105], v[90:91]
	v_add_f32_e32 v90, 0, v124
	v_add_f32_e32 v90, v125, v90
	v_add_f32_e32 v101, v126, v90
	v_mov_b32_e32 v90, v124
	v_mov_b32_e32 v91, v126
	v_mul_f32_e32 v98, v125, v125
	v_pk_fma_f32 v[90:91], v[90:91], v[90:91], v[98:99] op_sel_hi:[1,1,0]
	v_mul_f32_e32 v98, v126, v126
	v_pk_add_f32 v[90:91], v[90:91], v[98:99] op_sel_hi:[1,0]
	v_add_f32_e32 v98, v127, v101
	v_add_f32_e32 v101, v128, v98
	v_mul_f32_e32 v98, v127, v127
	v_mov_b32_e32 v106, v128
	v_mov_b32_e32 v107, v127
	v_pk_add_f32 v[90:91], v[98:99], v[90:91] op_sel_hi:[0,1]
	v_pk_mul_f32 v[94:95], v[86:87], v[86:87]
	v_pk_fma_f32 v[106:107], v[106:107], v[106:107], v[90:91]
	v_add_f32_e32 v90, v129, v101
	v_add_f32_e32 v91, v130, v90
	v_mul_f32_e32 v90, v129, v129
	v_mov_b32_e32 v110, v94
	v_mov_b32_e32 v111, v86
	v_pk_mul_f32 v[96:97], v[88:89], v[88:89]
	v_pk_add_f32 v[106:107], v[90:91], v[106:107] op_sel_hi:[0,1]
	v_and_b32_e32 v90, 64, v181
	v_pk_add_f32 v[92:93], v[92:93], v[110:111]
	v_mov_b32_e32 v94, v95
	v_mov_b32_e32 v95, v87
	v_add_u32_e32 v90, 64, v90
	v_xor_b32_e32 v98, 32, v181
	v_pk_add_f32 v[92:93], v[94:95], v[92:93]
	v_mov_b32_e32 v94, v96
	v_mov_b32_e32 v95, v88
	v_cmp_lt_i32_e32 vcc, v98, v90
	v_pk_add_f32 v[92:93], v[92:93], v[94:95]
	v_mov_b32_e32 v94, v97
	v_mov_b32_e32 v95, v89
	v_cndmask_b32_e32 v98, v181, v98, vcc
	v_pk_add_f32 v[92:93], v[94:95], v[92:93]
	v_lshlrev_b32_e32 v112, 2, v98
	v_cndmask_b32_e64 v93, 0, v93, s[38:39]
	v_cndmask_b32_e64 v92, 0, v92, s[38:39]
	ds_bpermute_b32 v95, v112, v93
	ds_bpermute_b32 v94, v112, v92
	v_xor_b32_e32 v98, 16, v181
	v_cmp_lt_i32_e32 vcc, v98, v90
	v_mov_b32_e32 v101, v147
	v_xor_b32_e32 v102, 2, v181
	v_cndmask_b32_e32 v98, v181, v98, vcc
	v_lshlrev_b32_e32 v113, 2, v98
	v_xor_b32_e32 v98, 8, v181
	v_cmp_lt_i32_e32 vcc, v98, v90
	s_waitcnt lgkmcnt(0)
	v_pk_add_f32 v[92:93], v[92:93], v[94:95]
	ds_bpermute_b32 v95, v113, v93
	v_cndmask_b32_e32 v96, v181, v98, vcc
	ds_bpermute_b32 v94, v113, v92
	v_lshlrev_b32_e32 v110, 2, v96
	v_xor_b32_e32 v96, 4, v181
	v_cmp_lt_i32_e32 vcc, v96, v90
	v_mul_f32_e32 v98, v147, v147
	s_waitcnt lgkmcnt(0)
	v_pk_add_f32 v[92:93], v[92:93], v[94:95]
	v_cndmask_b32_e32 v96, v181, v96, vcc
	v_lshlrev_b32_e32 v111, 2, v96
	v_pk_add_f32 v[96:97], v[100:101], v[98:99]
	ds_bpermute_b32 v95, v110, v93
	v_cndmask_b32_e64 v97, 0, v97, s[38:39]
	v_cndmask_b32_e64 v96, 0, v96, s[38:39]
	ds_bpermute_b32 v94, v110, v92
	ds_bpermute_b32 v99, v112, v97
	ds_bpermute_b32 v98, v112, v96
	v_cmp_lt_i32_e32 vcc, v102, v90
	v_mov_b32_e32 v108, v130
	s_waitcnt lgkmcnt(2)
	v_pk_add_f32 v[92:93], v[92:93], v[94:95]
	ds_bpermute_b32 v95, v111, v93
	s_waitcnt lgkmcnt(1)
	v_pk_add_f32 v[96:97], v[96:97], v[98:99]
	ds_bpermute_b32 v94, v111, v92
	ds_bpermute_b32 v99, v113, v97
	ds_bpermute_b32 v98, v113, v96
	v_cndmask_b32_e32 v100, v181, v102, vcc
	v_lshlrev_b32_e32 v116, 2, v100
	s_waitcnt lgkmcnt(2)
	v_pk_add_f32 v[92:93], v[92:93], v[94:95]
	ds_bpermute_b32 v95, v116, v93
	s_waitcnt lgkmcnt(1)
	v_pk_add_f32 v[96:97], v[96:97], v[98:99]
	ds_bpermute_b32 v94, v116, v92
	ds_bpermute_b32 v99, v110, v97
	ds_bpermute_b32 v98, v110, v96
	v_mov_b32_e32 v109, v129
	v_pk_fma_f32 v[100:101], v[108:109], v[108:109], v[106:107]
	s_waitcnt lgkmcnt(2)
	v_pk_add_f32 v[118:119], v[92:93], v[94:95]
	v_xor_b32_e32 v101, 1, v181
	s_waitcnt lgkmcnt(0)
	v_pk_add_f32 v[92:93], v[96:97], v[98:99]
	ds_bpermute_b32 v95, v111, v93
	ds_bpermute_b32 v94, v111, v92
	v_cmp_lt_i32_e32 vcc, v101, v90
	v_mov_b32_e32 v105, v139
	v_mul_f32_e32 v102, v139, v139
	v_cndmask_b32_e32 v90, v181, v101, vcc
	v_lshlrev_b32_e32 v108, 2, v90
	v_mov_b32_e32 v101, v131
	v_mul_f32_e32 v90, v131, v131
	s_waitcnt lgkmcnt(0)
	v_pk_add_f32 v[92:93], v[92:93], v[94:95]
	v_pk_add_f32 v[94:95], v[104:105], v[102:103]
	v_pk_add_f32 v[90:91], v[100:101], v[90:91]
	v_cndmask_b32_e64 v95, 0, v95, s[38:39]
	v_cndmask_b32_e64 v94, 0, v94, s[38:39]
	v_cndmask_b32_e64 v91, 0, v91, s[38:39]
	v_cndmask_b32_e64 v90, 0, v90, s[38:39]
	ds_bpermute_b32 v97, v112, v95
	ds_bpermute_b32 v96, v112, v94
	ds_bpermute_b32 v99, v112, v91
	ds_bpermute_b32 v98, v112, v90
	ds_bpermute_b32 v101, v116, v93
	ds_bpermute_b32 v100, v116, v92
	s_waitcnt lgkmcnt(4)
	v_pk_add_f32 v[94:95], v[94:95], v[96:97]
	ds_bpermute_b32 v97, v113, v95
	s_waitcnt lgkmcnt(3)
	v_pk_add_f32 v[90:91], v[90:91], v[98:99]
	ds_bpermute_b32 v96, v113, v94
	ds_bpermute_b32 v99, v113, v91
	ds_bpermute_b32 v98, v113, v90
	s_waitcnt lgkmcnt(4)
	v_pk_add_f32 v[114:115], v[92:93], v[100:101]
	ds_bpermute_b32 v121, v108, v119
	s_waitcnt lgkmcnt(3)
	v_pk_add_f32 v[94:95], v[94:95], v[96:97]
	ds_bpermute_b32 v97, v110, v95
	s_waitcnt lgkmcnt(2)
	v_pk_add_f32 v[90:91], v[90:91], v[98:99]
	ds_bpermute_b32 v96, v110, v94
	ds_bpermute_b32 v99, v110, v91
	ds_bpermute_b32 v98, v110, v90
	ds_bpermute_b32 v120, v108, v118
	ds_bpermute_b32 v117, v108, v115
	s_waitcnt lgkmcnt(4)
	v_pk_add_f32 v[92:93], v[94:95], v[96:97]
	ds_bpermute_b32 v95, v111, v93
	s_waitcnt lgkmcnt(3)
	v_pk_add_f32 v[90:91], v[90:91], v[98:99]
	ds_bpermute_b32 v94, v111, v92
	ds_bpermute_b32 v97, v111, v91
	ds_bpermute_b32 v96, v111, v90
	v_lshl_or_b32 v148, v148, 11, v154
	v_add_u32_e32 v123, 0x1000, v148
	s_waitcnt lgkmcnt(2)
	v_pk_add_f32 v[92:93], v[92:93], v[94:95]
	ds_bpermute_b32 v95, v116, v93
	s_waitcnt lgkmcnt(1)
	v_pk_add_f32 v[90:91], v[90:91], v[96:97]
	ds_bpermute_b32 v94, v116, v92
	ds_bpermute_b32 v97, v116, v91
	ds_bpermute_b32 v96, v116, v90
	ds_bpermute_b32 v116, v108, v114
	s_waitcnt lgkmcnt(3)
	v_pk_add_f32 v[110:111], v[92:93], v[94:95]
	ds_bpermute_b32 v113, v108, v111
	s_waitcnt lgkmcnt(2)
	v_pk_add_f32 v[106:107], v[90:91], v[96:97]
	ds_bpermute_b32 v112, v108, v110
	ds_bpermute_b32 v109, v108, v107
	ds_bpermute_b32 v108, v108, v106
	s_and_saveexec_b64 s[12:13], s[38:39]
	s_cbranch_execz .LBB0_842
	v_mov_b64_e32 v[90:91], v[194:195]
	v_mov_b64_e32 v[92:93], v[196:197]
	v_mov_b64_e32 v[98:99], v[198:199]
	v_mov_b64_e32 v[100:101], v[200:201]
	v_mov_b64_e32 v[94:95], v[202:203]
	v_mov_b64_e32 v[96:97], v[204:205]
	v_mov_b64_e32 v[102:103], v[206:207]
	v_mov_b64_e32 v[104:105], v[208:209]
	v_pk_add_f32 v[118:119], v[118:119], v[120:121]
	s_mov_b32 s2, 0x3b2aaaab
	v_pk_mul_f32 v[118:119], v[118:119], s[2:3] op_sel_hi:[1,0]
	v_and_b32_e32 v150, 0xffff0000, v81
	v_fma_f32 v118, -v119, v119, v118
	v_max_f32_e32 v118, 0, v118
	v_add_f32_e32 v118, 0x358637bd, v118
	v_cmp_gt_f32_e32 vcc, s33, v118
	v_mul_f32_e32 v120, 0x4b800000, v118
	v_cndmask_b32_e32 v118, v118, v120, vcc
	v_rsq_f32_e32 v118, v118
	s_nop 0
	v_mul_f32_e32 v120, 0x45800000, v118
	v_cndmask_b32_e32 v118, v118, v120, vcc
	v_mul_f32_e64 v248, -v119, v118
	v_fma_f32 v89, v89, v118, v248
	v_fma_f32 v88, v88, v118, v248
	v_fma_f32 v87, v87, v118, v248
	v_lshlrev_b32_e32 v81, 16, v81
	v_fma_f32 v86, v86, v118, v248
	v_fma_f32 v85, v85, v118, v248
	v_fma_f32 v84, v84, v118, v248
	v_fma_f32 v83, v83, v118, v248
	v_fma_f32 v82, v82, v118, v248
	s_mov_b32 s10, s66
	s_mov_b32 s11, s67
	v_fma_f32 v85, v85, v97, v93
	v_fma_f32 v89, v89, v105, v101
	v_mul_f32_e32 v120, 0xbfb8aa3b, v89
	v_exp_f32_e32 v120, v120
	v_fma_f32 v88, v88, v104, v100
	v_fma_f32 v87, v87, v103, v99
	v_fma_f32 v86, v86, v102, v98
	v_add_f32_e32 v120, 1.0, v120
	v_rcp_f32_e32 v120, v120
	v_fma_f32 v84, v84, v96, v92
	v_fma_f32 v83, v83, v95, v91
	v_fma_f32 v82, v82, v94, v90
	v_mul_f32_e32 v89, v89, v120
	v_mul_f32_e32 v120, 0xbfb8aa3b, v88
	v_exp_f32_e32 v120, v120
	v_mul_f32_e32 v89, v89, v150
	v_add_f32_e32 v120, 1.0, v120
	v_rcp_f32_e32 v120, v120
	s_nop 0
	v_mul_f32_e32 v88, v88, v120
	v_mul_f32_e32 v120, 0xbfb8aa3b, v87
	v_exp_f32_e32 v120, v120
	v_mul_f32_e32 v81, v88, v81
	v_and_b32_e32 v88, 0xffff0000, v80
	v_lshlrev_b32_e32 v80, 16, v80
	v_add_f32_e32 v120, 1.0, v120
	v_rcp_f32_e32 v120, v120
	s_nop 0
	v_mul_f32_e32 v87, v87, v120
	v_mul_f32_e32 v87, v87, v88
	v_mul_f32_e32 v88, 0xbfb8aa3b, v86
	v_exp_f32_e32 v88, v88
	s_nop 0
	v_add_f32_e32 v88, 1.0, v88
	v_rcp_f32_e32 v88, v88
	s_nop 0
	v_mul_f32_e32 v86, v86, v88
	v_mul_f32_e32 v88, 0xbfb8aa3b, v85
	v_exp_f32_e32 v88, v88
	v_mul_f32_e32 v80, v86, v80
	v_and_b32_e32 v86, 0xffff0000, v79
	v_lshlrev_b32_e32 v79, 16, v79
	v_add_f32_e32 v88, 1.0, v88
	v_rcp_f32_e32 v88, v88
	s_nop 0
	v_mul_f32_e32 v85, v85, v88
	v_mul_f32_e32 v85, v85, v86
	v_mul_f32_e32 v86, 0xbfb8aa3b, v84
	v_exp_f32_e32 v86, v86
	s_nop 0
	v_add_f32_e32 v86, 1.0, v86
	v_rcp_f32_e32 v86, v86
	s_nop 0
	v_mul_f32_e32 v84, v84, v86
	v_mul_f32_e32 v86, 0xbfb8aa3b, v83
	v_exp_f32_e32 v86, v86
	v_mul_f32_e32 v79, v84, v79
	v_and_b32_e32 v84, 0xffff0000, v78
	v_lshlrev_b32_e32 v78, 16, v78
	v_add_f32_e32 v86, 1.0, v86
	v_rcp_f32_e32 v86, v86
	s_nop 0
	v_mul_f32_e32 v83, v83, v86
	v_mul_f32_e32 v83, v83, v84
	v_mul_f32_e32 v84, 0xbfb8aa3b, v82
	v_exp_f32_e32 v84, v84
	s_nop 0
	v_add_f32_e32 v84, 1.0, v84
	v_rcp_f32_e32 v84, v84
	s_nop 0
	v_mul_f32_e32 v82, v82, v84
	v_mul_f32_e32 v78, v82, v78
	v_cvt_pk_bf16_f32 v78, v78, v83
	v_cvt_pk_bf16_f32 v79, v79, v85
	v_cvt_pk_bf16_f32 v80, v80, v87
	v_cvt_pk_bf16_f32 v81, v81, v89
	buffer_store_dwordx4 v[78:81], v148, s[8:11], 0 offen sc1
	s_waitcnt lgkmcnt(4)
	s_nop 0
	v_pk_add_f32 v[78:79], v[114:115], v[116:117]
	v_and_b32_e32 v80, 0xffff0000, v77
	v_pk_mul_f32 v[78:79], v[78:79], s[2:3] op_sel_hi:[1,0]
	v_lshlrev_b32_e32 v77, 16, v77
	v_fma_f32 v78, -v79, v79, v78
	v_max_f32_e32 v78, 0, v78
	v_add_f32_e32 v78, 0x358637bd, v78
	v_cmp_gt_f32_e32 vcc, s33, v78
	v_mul_f32_e32 v81, 0x4b800000, v78
	s_nop 0
	v_cndmask_b32_e32 v78, v78, v81, vcc
	v_rsq_f32_e32 v78, v78
	s_nop 0
	v_mul_f32_e32 v81, 0x45800000, v78
	v_cndmask_b32_e32 v78, v78, v81, vcc
	v_mul_f32_e64 v249, -v79, v78
	v_fma_f32 v81, v147, v78, v249
	v_fma_f32 v81, v81, v105, v101
	v_mul_f32_e32 v82, 0xbfb8aa3b, v81
	v_exp_f32_e32 v82, v82
	s_nop 0
	v_add_f32_e32 v82, 1.0, v82
	v_rcp_f32_e32 v82, v82
	s_nop 0
	v_mul_f32_e32 v81, v81, v82
	v_mul_f32_e32 v80, v81, v80
	v_fma_f32 v81, v146, v78, v249
	v_fma_f32 v81, v81, v104, v100
	v_mul_f32_e32 v82, 0xbfb8aa3b, v81
	v_exp_f32_e32 v82, v82
	s_nop 0
	v_add_f32_e32 v82, 1.0, v82
	v_rcp_f32_e32 v82, v82
	s_nop 0
	v_mul_f32_e32 v81, v81, v82
	v_fma_f32 v82, v145, v78, v249
	v_fma_f32 v82, v82, v103, v99
	v_mul_f32_e32 v83, 0xbfb8aa3b, v82
	v_exp_f32_e32 v83, v83
	v_mul_f32_e32 v77, v81, v77
	v_and_b32_e32 v81, 0xffff0000, v76
	v_lshlrev_b32_e32 v76, 16, v76
	v_add_f32_e32 v83, 1.0, v83
	v_rcp_f32_e32 v83, v83
	s_nop 0
	v_mul_f32_e32 v82, v82, v83
	v_mul_f32_e32 v81, v82, v81
	v_fma_f32 v82, v144, v78, v249
	v_fma_f32 v82, v82, v102, v98
	v_mul_f32_e32 v83, 0xbfb8aa3b, v82
	v_exp_f32_e32 v83, v83
	s_nop 0
	v_add_f32_e32 v83, 1.0, v83
	v_rcp_f32_e32 v83, v83
	s_nop 0
	v_mul_f32_e32 v82, v82, v83
	v_fma_f32 v83, v143, v78, v249
	v_fma_f32 v83, v83, v97, v93
	v_mul_f32_e32 v84, 0xbfb8aa3b, v83
	v_exp_f32_e32 v84, v84
	v_mul_f32_e32 v76, v82, v76
	v_and_b32_e32 v82, 0xffff0000, v75
	v_lshlrev_b32_e32 v75, 16, v75
	v_add_f32_e32 v84, 1.0, v84
	v_rcp_f32_e32 v84, v84
	s_nop 0
	v_mul_f32_e32 v83, v83, v84
	v_mul_f32_e32 v82, v83, v82
	v_fma_f32 v83, v142, v78, v249
	v_fma_f32 v83, v83, v96, v92
	v_mul_f32_e32 v84, 0xbfb8aa3b, v83
	v_exp_f32_e32 v84, v84
	s_nop 0
	v_add_f32_e32 v84, 1.0, v84
	v_rcp_f32_e32 v84, v84
	s_nop 0
	v_mul_f32_e32 v83, v83, v84
	v_fma_f32 v84, v141, v78, v249
	v_fma_f32 v78, v140, v78, v249
	v_fma_f32 v78, v78, v94, v90
	v_fma_f32 v84, v84, v95, v91
	v_mul_f32_e32 v79, 0xbfb8aa3b, v78
	v_mul_f32_e32 v85, 0xbfb8aa3b, v84
	v_exp_f32_e32 v79, v79
	v_exp_f32_e32 v85, v85
	v_mul_f32_e32 v75, v83, v75
	v_and_b32_e32 v83, 0xffff0000, v74
	v_add_f32_e32 v79, 1.0, v79
	v_add_f32_e32 v85, 1.0, v85
	v_rcp_f32_e32 v79, v79
	v_rcp_f32_e32 v85, v85
	v_lshlrev_b32_e32 v74, 16, v74
	v_mul_f32_e32 v78, v78, v79
	v_mul_f32_e32 v84, v84, v85
	v_mul_f32_e32 v74, v78, v74
	v_mul_f32_e32 v83, v84, v83
	v_cvt_pk_bf16_f32 v74, v74, v83
	v_cvt_pk_bf16_f32 v75, v75, v82
	v_cvt_pk_bf16_f32 v76, v76, v81
	v_cvt_pk_bf16_f32 v77, v77, v80
	buffer_store_dwordx4 v[74:77], v148, s[8:11], 0 offen offset:2048 sc1
	s_waitcnt lgkmcnt(2)
	s_nop 0
	v_pk_add_f32 v[74:75], v[110:111], v[112:113]
	v_and_b32_e32 v76, 0xffff0000, v73
	v_pk_mul_f32 v[74:75], v[74:75], s[2:3] op_sel_hi:[1,0]
	v_lshlrev_b32_e32 v73, 16, v73
	v_fma_f32 v74, -v75, v75, v74
	v_max_f32_e32 v74, 0, v74
	v_add_f32_e32 v74, 0x358637bd, v74
	v_cmp_gt_f32_e32 vcc, s33, v74
	v_mul_f32_e32 v77, 0x4b800000, v74
	s_nop 0
	v_cndmask_b32_e32 v74, v74, v77, vcc
	v_rsq_f32_e32 v74, v74
	s_nop 0
	v_mul_f32_e32 v77, 0x45800000, v74
	v_cndmask_b32_e32 v74, v74, v77, vcc
	v_mul_f32_e64 v250, -v75, v74
	v_fma_f32 v77, v139, v74, v250
	v_fma_f32 v77, v77, v105, v101
	v_mul_f32_e32 v78, 0xbfb8aa3b, v77
	v_exp_f32_e32 v78, v78
	s_nop 0
	v_add_f32_e32 v78, 1.0, v78
	v_rcp_f32_e32 v78, v78
	s_nop 0
	v_mul_f32_e32 v77, v77, v78
	v_mul_f32_e32 v76, v77, v76
	v_fma_f32 v77, v138, v74, v250
	v_fma_f32 v77, v77, v104, v100
	v_mul_f32_e32 v78, 0xbfb8aa3b, v77
	v_exp_f32_e32 v78, v78
	s_nop 0
	v_add_f32_e32 v78, 1.0, v78
	v_rcp_f32_e32 v78, v78
	s_nop 0
	v_mul_f32_e32 v77, v77, v78
	v_fma_f32 v78, v137, v74, v250
	v_fma_f32 v78, v78, v103, v99
	v_mul_f32_e32 v79, 0xbfb8aa3b, v78
	v_exp_f32_e32 v79, v79
	v_mul_f32_e32 v73, v77, v73
	v_and_b32_e32 v77, 0xffff0000, v72
	v_lshlrev_b32_e32 v72, 16, v72
	v_add_f32_e32 v79, 1.0, v79
	v_rcp_f32_e32 v79, v79
	s_nop 0
	v_mul_f32_e32 v78, v78, v79
	v_mul_f32_e32 v77, v78, v77
	v_fma_f32 v78, v136, v74, v250
	v_fma_f32 v78, v78, v102, v98
	v_mul_f32_e32 v79, 0xbfb8aa3b, v78
	v_exp_f32_e32 v79, v79
	s_nop 0
	v_add_f32_e32 v79, 1.0, v79
	v_rcp_f32_e32 v79, v79
	s_nop 0
	v_mul_f32_e32 v78, v78, v79
	v_fma_f32 v79, v135, v74, v250
	v_fma_f32 v79, v79, v97, v93
	v_mul_f32_e32 v80, 0xbfb8aa3b, v79
	v_exp_f32_e32 v80, v80
	v_mul_f32_e32 v72, v78, v72
	v_and_b32_e32 v78, 0xffff0000, v71
	v_lshlrev_b32_e32 v71, 16, v71
	v_add_f32_e32 v80, 1.0, v80
	v_rcp_f32_e32 v80, v80
	s_nop 0
	v_mul_f32_e32 v79, v79, v80
	v_mul_f32_e32 v78, v79, v78
	v_fma_f32 v79, v134, v74, v250
	v_fma_f32 v79, v79, v96, v92
	v_mul_f32_e32 v80, 0xbfb8aa3b, v79
	v_exp_f32_e32 v80, v80
	s_nop 0
	v_add_f32_e32 v80, 1.0, v80
	v_rcp_f32_e32 v80, v80
	s_nop 0
	v_mul_f32_e32 v79, v79, v80
	v_fma_f32 v80, v133, v74, v250
	v_fma_f32 v74, v132, v74, v250
	v_fma_f32 v74, v74, v94, v90
	v_fma_f32 v80, v80, v95, v91
	v_mul_f32_e32 v75, 0xbfb8aa3b, v74
	v_mul_f32_e32 v81, 0xbfb8aa3b, v80
	v_exp_f32_e32 v75, v75
	v_exp_f32_e32 v81, v81
	v_mul_f32_e32 v71, v79, v71
	v_and_b32_e32 v79, 0xffff0000, v70
	v_add_f32_e32 v75, 1.0, v75
	v_add_f32_e32 v81, 1.0, v81
	v_rcp_f32_e32 v75, v75
	v_rcp_f32_e32 v81, v81
	v_lshlrev_b32_e32 v70, 16, v70
	v_mul_f32_e32 v74, v74, v75
	v_mul_f32_e32 v80, v80, v81
	v_mul_f32_e32 v70, v74, v70
	v_mul_f32_e32 v79, v80, v79
	v_cvt_pk_bf16_f32 v70, v70, v79
	v_cvt_pk_bf16_f32 v71, v71, v78
	v_cvt_pk_bf16_f32 v72, v72, v77
	v_cvt_pk_bf16_f32 v73, v73, v76
	buffer_store_dwordx4 v[70:73], v123, s[8:11], 0 offen sc1
	s_waitcnt lgkmcnt(0)
	s_nop 0
	v_pk_add_f32 v[70:71], v[106:107], v[108:109]
	v_and_b32_e32 v72, 0xffff0000, v61
	v_pk_mul_f32 v[70:71], v[70:71], s[2:3] op_sel_hi:[1,0]
	v_lshlrev_b32_e32 v61, 16, v61
	v_fma_f32 v70, -v71, v71, v70
	v_max_f32_e32 v70, 0, v70
	v_add_f32_e32 v70, 0x358637bd, v70
	v_cmp_gt_f32_e32 vcc, s33, v70
	v_mul_f32_e32 v73, 0x4b800000, v70
	s_nop 0
	v_cndmask_b32_e32 v70, v70, v73, vcc
	v_rsq_f32_e32 v70, v70
	s_nop 0
	v_mul_f32_e32 v73, 0x45800000, v70
	v_cndmask_b32_e32 v70, v70, v73, vcc
	v_mul_f32_e64 v251, -v71, v70
	v_fma_f32 v73, v131, v70, v251
	v_fma_f32 v73, v73, v105, v101
	v_mul_f32_e32 v74, 0xbfb8aa3b, v73
	v_exp_f32_e32 v74, v74
	s_nop 0
	v_add_f32_e32 v74, 1.0, v74
	v_rcp_f32_e32 v74, v74
	s_nop 0
	v_mul_f32_e32 v73, v73, v74
	v_mul_f32_e32 v72, v73, v72
	v_fma_f32 v73, v130, v70, v251
	v_fma_f32 v73, v73, v104, v100
	v_mul_f32_e32 v74, 0xbfb8aa3b, v73
	v_exp_f32_e32 v74, v74
	s_nop 0
	v_add_f32_e32 v74, 1.0, v74
	v_rcp_f32_e32 v74, v74
	s_nop 0
	v_mul_f32_e32 v73, v73, v74
	v_fma_f32 v74, v129, v70, v251
	v_fma_f32 v74, v74, v103, v99
	v_mul_f32_e32 v75, 0xbfb8aa3b, v74
	v_exp_f32_e32 v75, v75
	v_mul_f32_e32 v61, v73, v61
	v_and_b32_e32 v73, 0xffff0000, v60
	v_lshlrev_b32_e32 v60, 16, v60
	v_add_f32_e32 v75, 1.0, v75
	v_rcp_f32_e32 v75, v75
	s_nop 0
	v_mul_f32_e32 v74, v74, v75
	v_mul_f32_e32 v73, v74, v73
	v_fma_f32 v74, v128, v70, v251
	v_fmac_f32_e32 v98, v74, v102
	v_fma_f32 v75, v127, v70, v251
	v_mul_f32_e32 v74, 0xbfb8aa3b, v98
	v_fma_f32 v75, v75, v97, v93
	v_exp_f32_e32 v74, v74
	v_mul_f32_e32 v76, 0xbfb8aa3b, v75
	v_exp_f32_e32 v76, v76
	v_add_f32_e32 v74, 1.0, v74
	v_rcp_f32_e32 v74, v74
	v_add_f32_e32 v76, 1.0, v76
	v_rcp_f32_e32 v76, v76
	v_mul_f32_e32 v74, v98, v74
	v_mul_f32_e32 v60, v74, v60
	v_and_b32_e32 v74, 0xffff0000, v59
	v_mul_f32_e32 v75, v75, v76
	v_mul_f32_e32 v74, v75, v74
	v_fma_f32 v75, v126, v70, v251
	v_fma_f32 v75, v75, v96, v92
	v_mul_f32_e32 v76, 0xbfb8aa3b, v75
	v_exp_f32_e32 v76, v76
	v_lshlrev_b32_e32 v59, 16, v59
	v_add_f32_e32 v76, 1.0, v76
	v_rcp_f32_e32 v76, v76
	s_nop 0
	v_mul_f32_e32 v75, v75, v76
	v_fma_f32 v76, v125, v70, v251
	v_fma_f32 v70, v124, v70, v251
	v_fmac_f32_e32 v90, v70, v94
	v_fma_f32 v76, v76, v95, v91
	v_mul_f32_e32 v70, 0xbfb8aa3b, v90
	v_mul_f32_e32 v77, 0xbfb8aa3b, v76
	v_exp_f32_e32 v70, v70
	v_exp_f32_e32 v77, v77
	v_mul_f32_e32 v59, v75, v59
	v_and_b32_e32 v75, 0xffff0000, v58
	v_add_f32_e32 v70, 1.0, v70
	v_add_f32_e32 v77, 1.0, v77
	v_rcp_f32_e32 v70, v70
	v_rcp_f32_e32 v77, v77
	v_lshlrev_b32_e32 v58, 16, v58
	v_mul_f32_e32 v70, v90, v70
	v_mul_f32_e32 v76, v76, v77
	v_mul_f32_e32 v58, v70, v58
	v_mul_f32_e32 v75, v76, v75
	v_cvt_pk_bf16_f32 v58, v58, v75
	v_cvt_pk_bf16_f32 v59, v59, v74
	v_cvt_pk_bf16_f32 v60, v60, v73
	v_cvt_pk_bf16_f32 v61, v61, v72
	buffer_store_dwordx4 v[58:61], v123, s[8:11], 0 offen offset:2048 sc1
